# P0b row norm rewritten by hand as a looped depth-4 software-pipelined stream (contiguous 32 rows per wave, g/scale/shift hoisted); same f32 math
# speedup vs baseline: 1.0060x; 1.0060x over previous
.LBB0_109:
	s_or_b64 exec, exec, s[0:1]
	s_cmp_gt_i32 s4, 0xffff
	v_mbcnt_lo_u32_b32 v1, -1, 0
	s_cbranch_scc1 .LBB0_112
	s_cmpk_eq_u32 s54, 0x800
	s_cbranch_scc1 .Lnorm_fast
	v_mbcnt_hi_u32_b32 v2, -1, v1
	v_and_b32_e32 v3, 64, v2
	v_add_u32_e32 v3, 64, v3
	v_xor_b32_e32 v4, 1, v2
	v_cmp_lt_i32_e32 vcc, v4, v3
	s_ashr_i32 s5, s4, 31
	s_lshl_b64 s[0:1], s[4:5], 11
	v_cndmask_b32_e32 v4, v2, v4, vcc
	v_lshlrev_b32_e32 v12, 2, v4
	v_xor_b32_e32 v4, 2, v2
	v_cmp_lt_i32_e32 vcc, v4, v3
	v_mov_b32_e32 v5, 0
	s_add_u32 s0, s26, s0
	v_cndmask_b32_e32 v4, v2, v4, vcc
	v_lshlrev_b32_e32 v13, 2, v4
	v_xor_b32_e32 v4, 4, v2
	v_cmp_lt_i32_e32 vcc, v4, v3
	v_lshlrev_b32_e32 v8, 3, v9
	s_addc_u32 s1, s27, s1
	v_cndmask_b32_e32 v4, v2, v4, vcc
	v_lshlrev_b32_e32 v14, 2, v4
	v_xor_b32_e32 v4, 8, v2
	v_cmp_lt_i32_e32 vcc, v4, v3
	s_ashr_i32 s55, s54, 31
	s_lshl_b64 s[8:9], s[54:55], 11
	v_cndmask_b32_e32 v4, v2, v4, vcc
	v_lshlrev_b32_e32 v15, 2, v4
	v_xor_b32_e32 v4, 16, v2
	v_cmp_lt_i32_e32 vcc, v4, v3
	v_mov_b32_e32 v18, 0x358637bd
	v_mov_b32_e32 v19, 0x260
	v_cndmask_b32_e32 v4, v2, v4, vcc
	v_lshlrev_b32_e32 v16, 2, v4
	v_xor_b32_e32 v4, 32, v2
	v_cmp_lt_i32_e32 vcc, v4, v3
	s_nop 1
	v_cndmask_b32_e32 v2, v2, v4, vcc
	v_lshlrev_b32_e32 v17, 2, v2
	v_lshlrev_b32_e32 v2, 2, v9
	v_lshlrev_b32_e32 v4, 4, v9
	v_mov_b32_e32 v9, v5
	v_lshl_add_u64 v[8:9], s[0:1], 0, v[8:9]
	s_mov_b64 s[0:1], 0x4000000
	v_lshl_add_u64 v[8:9], v[8:9], 0, s[0:1]
	s_lshl_b64 s[0:1], s[4:5], 12
	s_add_u32 s0, s36, s0
	s_addc_u32 s1, s37, s1
	v_lshl_add_u64 v[6:7], s[44:45], 0, v[4:5]
	v_or_b32_e32 v22, 0x100, v2
	v_or_b32_e32 v24, 0x200, v2
	v_or_b32_e32 v26, 0x300, v2
	v_lshl_add_u64 v[4:5], s[0:1], 0, v[4:5]
	s_mov_b64 s[0:1], 0xc00
	v_lshl_add_u64 v[10:11], v[4:5], 0, s[0:1]
	s_lshl_b64 s[12:13], s[54:55], 12
	s_mov_b32 s5, 0xf800000
	v_lshlrev_b32_e32 v20, 2, v2
	v_lshlrev_b32_e32 v21, 2, v22
	v_lshlrev_b32_e32 v22, 2, v24
	v_lshlrev_b32_e32 v23, 2, v26
.LBB0_111:
	global_load_dwordx4 v[24:27], v[10:11], off offset:-3072
	global_load_dwordx4 v[28:31], v[10:11], off offset:-2048
	global_load_dwordx4 v[2:5], v[10:11], off
	global_load_dwordx4 v[32:35], v[10:11], off offset:-1024
	s_ashr_i32 s0, s4, 11
	s_mul_hi_i32 s1, s0, 0x6000
	s_mulk_i32 s0, 0x6000
	s_add_u32 s14, s68, s0
	s_addc_u32 s15, s69, s1
	s_add_u32 s18, s14, 0x1000
	global_load_dwordx4 v[36:39], v[6:7], off
	s_addc_u32 s19, s15, 0
	global_load_dwordx4 v[40:43], v20, s[18:19]
	global_load_dwordx4 v[44:47], v20, s[14:15]
	s_add_i32 s4, s4, s54
	v_lshl_add_u64 v[10:11], v[10:11], 0, s[12:13]
	s_cmp_lt_i32 s4, 0x10000
	s_waitcnt vmcnt(6)
	v_pk_mul_f32 v[48:49], v[26:27], v[26:27]
	v_pk_mul_f32 v[50:51], v[24:25], v[24:25]
	s_waitcnt vmcnt(5)
	v_pk_mul_f32 v[52:53], v[30:31], v[30:31]
	v_pk_mul_f32 v[54:55], v[28:29], v[28:29]
	v_pk_mov_b32 v[60:61], v[50:51], v[48:49] op_sel:[1,0]
	v_mov_b32_e32 v51, v49
	v_pk_mov_b32 v[48:49], v[54:55], v[52:53] op_sel:[1,0]
	v_mov_b32_e32 v55, v53
	s_waitcnt vmcnt(4)
	v_mul_f32_e32 v59, v2, v2
	s_waitcnt vmcnt(3)
	v_mul_f32_e32 v56, v33, v33
	v_mul_f32_e32 v58, v35, v35
	v_pk_add_f32 v[50:51], v[60:61], v[50:51]
	v_pk_add_f32 v[48:49], v[48:49], v[54:55]
	v_mul_f32_e32 v62, v3, v3
	v_mul_f32_e32 v63, v4, v4
	v_mul_f32_e32 v64, v5, v5
	v_pk_fma_f32 v[52:53], v[32:33], v[32:33], v[56:57] op_sel_hi:[1,1,0]
	v_pk_fma_f32 v[56:57], v[34:35], v[34:35], v[58:59] op_sel_hi:[1,1,0]
	v_pk_add_f32 v[50:51], v[50:51], v[50:51] op_sel:[0,1] op_sel_hi:[1,0]
	v_pk_add_f32 v[48:49], v[48:49], v[48:49] op_sel:[0,1] op_sel_hi:[1,0]
	v_mov_b32_e32 v53, v63
	v_mov_b32_e32 v57, v64
	v_mov_b32_e32 v51, v59
	v_mov_b32_e32 v49, v62
	v_pk_add_f32 v[52:53], v[52:53], v[56:57]
	v_pk_add_f32 v[48:49], v[50:51], v[48:49]
	s_waitcnt vmcnt(1)
	v_pk_add_f32 v[40:41], v[40:41], 1.0 op_sel_hi:[1,0]
	v_pk_add_f32 v[48:49], v[48:49], v[52:53]
	v_pk_add_f32 v[42:43], v[42:43], 1.0 op_sel_hi:[1,0]
	v_add_f32_e32 v48, v48, v49
	ds_bpermute_b32 v49, v12, v48
	s_waitcnt lgkmcnt(0)
	v_add_f32_e32 v48, v48, v49
	ds_bpermute_b32 v49, v13, v48
	s_waitcnt lgkmcnt(0)
	v_add_f32_e32 v48, v48, v49
	ds_bpermute_b32 v49, v14, v48
	s_waitcnt lgkmcnt(0)
	v_add_f32_e32 v48, v48, v49
	ds_bpermute_b32 v49, v15, v48
	s_waitcnt lgkmcnt(0)
	v_add_f32_e32 v48, v48, v49
	ds_bpermute_b32 v49, v16, v48
	s_waitcnt lgkmcnt(0)
	v_add_f32_e32 v48, v48, v49
	ds_bpermute_b32 v49, v17, v48
	s_waitcnt lgkmcnt(0)
	v_add_f32_e32 v48, v48, v49
	v_fmamk_f32 v48, v48, 0x3a800000, v18
	v_mul_f32_e32 v49, 0x4f800000, v48
	v_cmp_gt_f32_e32 vcc, s5, v48
	s_nop 1
	v_cndmask_b32_e32 v48, v48, v49, vcc
	v_sqrt_f32_e32 v49, v48
	s_nop 0
	v_add_u32_e32 v50, -1, v49
	v_add_u32_e32 v51, 1, v49
	v_fma_f32 v52, -v50, v49, v48
	v_fma_f32 v53, -v51, v49, v48
	v_cmp_ge_f32_e64 s[0:1], 0, v52
	s_nop 1
	v_cndmask_b32_e64 v49, v49, v50, s[0:1]
	v_cmp_lt_f32_e64 s[0:1], 0, v53
	s_nop 1
	v_cndmask_b32_e64 v49, v49, v51, s[0:1]
	v_mul_f32_e32 v50, 0x37800000, v49
	v_cndmask_b32_e32 v49, v49, v50, vcc
	v_cmp_class_f32_e32 vcc, v48, v19
	s_nop 1
	v_cndmask_b32_e32 v48, v49, v48, vcc
	v_div_scale_f32 v49, s[0:1], v48, v48, 1.0
	v_rcp_f32_e32 v51, v49
	v_div_scale_f32 v50, vcc, 1.0, v48, 1.0
	v_fma_f32 v52, -v49, v51, 1.0
	v_fmac_f32_e32 v51, v52, v51
	v_mul_f32_e32 v52, v50, v51
	v_fma_f32 v53, -v49, v52, v50
	v_fmac_f32_e32 v52, v53, v51
	v_fma_f32 v49, -v49, v52, v50
	v_div_fmas_f32 v49, v49, v51, v52
	v_div_fixup_f32 v48, v49, v48, 1.0
	v_pk_mul_f32 v[24:25], v[24:25], v[48:49] op_sel_hi:[1,0]
	v_pk_mul_f32 v[26:27], v[26:27], v[48:49] op_sel_hi:[1,0]
	v_pk_mul_f32 v[24:25], v[36:37], v[24:25]
	v_pk_mul_f32 v[26:27], v[38:39], v[26:27]
	s_waitcnt vmcnt(0)
	v_pk_fma_f32 v[24:25], v[40:41], v[24:25], v[44:45]
	v_pk_fma_f32 v[26:27], v[42:43], v[26:27], v[46:47]
	v_cvt_pk_bf16_f32 v24, v24, v25
	v_pk_mul_f32 v[30:31], v[30:31], v[48:49] op_sel_hi:[1,0]
	v_cvt_pk_bf16_f32 v25, v26, v27
	global_store_dwordx2 v[8:9], v[24:25], off
	global_load_dwordx4 v[24:27], v[6:7], off offset:1024
	s_nop 0
	global_load_dwordx4 v[36:39], v21, s[18:19]
	global_load_dwordx4 v[40:43], v20, s[14:15] offset:1024
	v_pk_mul_f32 v[28:29], v[28:29], v[48:49] op_sel_hi:[1,0]
	v_pk_mul_f32 v[32:33], v[32:33], v[48:49] op_sel_hi:[1,0]
	v_pk_mul_f32 v[34:35], v[34:35], v[48:49] op_sel_hi:[1,0]
	v_pk_mul_f32 v[4:5], v[4:5], v[48:49] op_sel_hi:[1,0]
	v_pk_mul_f32 v[2:3], v[2:3], v[48:49] op_sel_hi:[1,0]
	s_waitcnt vmcnt(2)
	v_pk_mul_f32 v[24:25], v[24:25], v[28:29]
	v_pk_mul_f32 v[26:27], v[26:27], v[30:31]
	s_waitcnt vmcnt(1)
	v_pk_add_f32 v[30:31], v[36:37], 1.0 op_sel_hi:[1,0]
	v_pk_add_f32 v[28:29], v[38:39], 1.0 op_sel_hi:[1,0]
	s_waitcnt vmcnt(0)
	v_pk_fma_f32 v[24:25], v[30:31], v[24:25], v[40:41]
	v_pk_fma_f32 v[26:27], v[28:29], v[26:27], v[42:43]
	v_cvt_pk_bf16_f32 v24, v24, v25
	s_nop 0
	v_cvt_pk_bf16_f32 v25, v26, v27
	global_store_dwordx2 v[8:9], v[24:25], off offset:512
	global_load_dwordx4 v[24:27], v[6:7], off offset:2048
	s_nop 0
	global_load_dwordx4 v[28:31], v22, s[18:19]
	global_load_dwordx4 v[36:39], v20, s[14:15] offset:2048
	s_waitcnt vmcnt(2)
	v_pk_mul_f32 v[24:25], v[32:33], v[24:25]
	s_waitcnt vmcnt(1)
	v_pk_add_f32 v[28:29], v[28:29], 1.0 op_sel_hi:[1,0]
	v_pk_mul_f32 v[26:27], v[34:35], v[26:27]
	v_pk_add_f32 v[30:31], v[30:31], 1.0 op_sel_hi:[1,0]
	s_waitcnt vmcnt(0)
	v_pk_fma_f32 v[24:25], v[24:25], v[28:29], v[36:37]
	v_pk_fma_f32 v[26:27], v[26:27], v[30:31], v[38:39]
	v_cvt_pk_bf16_f32 v24, v24, v25
	s_nop 0
	v_cvt_pk_bf16_f32 v25, v26, v27
	global_store_dwordx2 v[8:9], v[24:25], off offset:1024
	global_load_dwordx4 v[24:27], v[6:7], off offset:3072
	s_nop 0
	global_load_dwordx4 v[28:31], v23, s[18:19]
	global_load_dwordx4 v[32:35], v20, s[14:15] offset:3072
	s_waitcnt vmcnt(2)
	v_pk_mul_f32 v[2:3], v[2:3], v[24:25]
	v_pk_mul_f32 v[4:5], v[4:5], v[26:27]
	s_waitcnt vmcnt(1)
	v_pk_add_f32 v[26:27], v[28:29], 1.0 op_sel_hi:[1,0]
	v_pk_add_f32 v[24:25], v[30:31], 1.0 op_sel_hi:[1,0]
	s_waitcnt vmcnt(0)
	v_pk_fma_f32 v[2:3], v[2:3], v[26:27], v[32:33]
	v_pk_fma_f32 v[4:5], v[4:5], v[24:25], v[34:35]
	v_cvt_pk_bf16_f32 v2, v2, v3
	s_nop 0
	v_cvt_pk_bf16_f32 v3, v4, v5
	global_store_dwordx2 v[8:9], v[2:3], off offset:1536
	v_lshl_add_u64 v[8:9], v[8:9], 0, s[8:9]
	s_cbranch_scc1 .LBB0_111
	s_branch .LBB0_112
.Lnorm_fast:
	v_lshlrev_b32_e32 v2, 4, v9
	v_lshlrev_b32_e32 v3, 3, v9
	s_lshl_b32 s0, s4, 17
	s_add_u32 s8, s36, s0
	s_addc_u32 s9, s37, 0
	s_lshl_b32 s0, s4, 16
	s_add_u32 s12, s26, s0
	s_addc_u32 s13, s27, 0
	s_add_u32 s12, s12, 0x4000000
	s_addc_u32 s13, s13, 0
	s_lshr_b32 s0, s4, 6
	s_mul_i32 s0, s0, 0x6000
	s_add_u32 s14, s68, s0
	s_addc_u32 s15, s69, 0
	s_add_u32 s18, s14, 0x1000
	s_addc_u32 s19, s15, 0
	s_mov_b32 s5, 0xf800000
	v_mov_b32_e32 v110, 0x358637bd
	v_mov_b32_e32 v111, 0x260
	global_load_dwordx4 v[4:7], v2, s[44:45]
	global_load_dwordx4 v[20:23], v2, s[18:19]
	global_load_dwordx4 v[36:39], v2, s[14:15]
	global_load_dwordx4 v[8:11], v2, s[44:45] offset:1024
	global_load_dwordx4 v[24:27], v2, s[18:19] offset:1024
	global_load_dwordx4 v[40:43], v2, s[14:15] offset:1024
	global_load_dwordx4 v[12:15], v2, s[44:45] offset:2048
	global_load_dwordx4 v[28:31], v2, s[18:19] offset:2048
	global_load_dwordx4 v[44:47], v2, s[14:15] offset:2048
	global_load_dwordx4 v[16:19], v2, s[44:45] offset:3072
	global_load_dwordx4 v[32:35], v2, s[18:19] offset:3072
	global_load_dwordx4 v[48:51], v2, s[14:15] offset:3072
	s_add_u32 s18, s26, 0x2800000
	s_addc_u32 s19, s27, 0
	global_store_dwordx2 v3, v[116:117], s[18:19]
	global_store_dwordx2 v3, v[118:119], s[18:19]
	global_store_dwordx2 v3, v[120:121], s[18:19]
	global_store_dwordx2 v3, v[122:123], s[18:19]
	global_load_dwordx4 v[52:55], v2, s[8:9]
	global_load_dwordx4 v[56:59], v2, s[8:9] offset:1024
	global_load_dwordx4 v[60:63], v2, s[8:9] offset:2048
	global_load_dwordx4 v[64:67], v2, s[8:9] offset:3072
	s_add_u32 s8, s8, 0x1000
	s_addc_u32 s9, s9, 0
	global_store_dwordx2 v3, v[116:117], s[18:19]
	global_store_dwordx2 v3, v[118:119], s[18:19]
	global_store_dwordx2 v3, v[120:121], s[18:19]
	global_store_dwordx2 v3, v[122:123], s[18:19]
	global_load_dwordx4 v[68:71], v2, s[8:9]
	global_load_dwordx4 v[72:75], v2, s[8:9] offset:1024
	global_load_dwordx4 v[76:79], v2, s[8:9] offset:2048
	global_load_dwordx4 v[80:83], v2, s[8:9] offset:3072
	s_add_u32 s8, s8, 0x1000
	s_addc_u32 s9, s9, 0
	global_store_dwordx2 v3, v[116:117], s[18:19]
	global_store_dwordx2 v3, v[118:119], s[18:19]
	global_store_dwordx2 v3, v[120:121], s[18:19]
	global_store_dwordx2 v3, v[122:123], s[18:19]
	global_load_dwordx4 v[84:87], v2, s[8:9]
	global_load_dwordx4 v[88:91], v2, s[8:9] offset:1024
	global_load_dwordx4 v[92:95], v2, s[8:9] offset:2048
	global_load_dwordx4 v[96:99], v2, s[8:9] offset:3072
	s_add_u32 s8, s8, 0x1000
	s_addc_u32 s9, s9, 0
	global_store_dwordx2 v3, v[116:117], s[18:19]
	global_store_dwordx2 v3, v[118:119], s[18:19]
	global_store_dwordx2 v3, v[120:121], s[18:19]
	global_store_dwordx2 v3, v[122:123], s[18:19]
	global_load_dwordx4 v[124:127], v2, s[8:9]
	global_load_dwordx4 v[128:131], v2, s[8:9] offset:1024
	global_load_dwordx4 v[132:135], v2, s[8:9] offset:2048
	global_load_dwordx4 v[136:139], v2, s[8:9] offset:3072
	s_add_u32 s8, s8, 0x1000
	s_addc_u32 s9, s9, 0
	s_waitcnt vmcnt(32)
	v_pk_add_f32 v[20:21], v[20:21], 1.0 op_sel_hi:[1,0]
	v_pk_add_f32 v[22:23], v[22:23], 1.0 op_sel_hi:[1,0]
	v_pk_add_f32 v[24:25], v[24:25], 1.0 op_sel_hi:[1,0]
	v_pk_add_f32 v[26:27], v[26:27], 1.0 op_sel_hi:[1,0]
	v_pk_add_f32 v[28:29], v[28:29], 1.0 op_sel_hi:[1,0]
	v_pk_add_f32 v[30:31], v[30:31], 1.0 op_sel_hi:[1,0]
	v_pk_add_f32 v[32:33], v[32:33], 1.0 op_sel_hi:[1,0]
	v_pk_add_f32 v[34:35], v[34:35], 1.0 op_sel_hi:[1,0]
	s_mov_b32 s4, 0
.Lnorm_fast_loop:
	s_waitcnt vmcnt(24)
	v_pk_mul_f32 v[100:101], v[52:53], v[52:53]
	v_pk_fma_f32 v[100:101], v[54:55], v[54:55], v[100:101]
	v_pk_fma_f32 v[100:101], v[56:57], v[56:57], v[100:101]
	v_pk_fma_f32 v[100:101], v[58:59], v[58:59], v[100:101]
	v_pk_fma_f32 v[100:101], v[60:61], v[60:61], v[100:101]
	v_pk_fma_f32 v[100:101], v[62:63], v[62:63], v[100:101]
	v_pk_fma_f32 v[100:101], v[64:65], v[64:65], v[100:101]
	v_pk_fma_f32 v[100:101], v[66:67], v[66:67], v[100:101]
	v_add_f32_e32 v102, v100, v101
	s_nop 1
	v_add_f32_dpp v103, v102, v102 quad_perm:[1,0,3,2] row_mask:0xf bank_mask:0xf
	s_nop 1
	v_add_f32_dpp v102, v103, v103 quad_perm:[2,3,0,1] row_mask:0xf bank_mask:0xf
	s_nop 1
	v_add_f32_dpp v103, v102, v102 row_ror:4 row_mask:0xf bank_mask:0xf
	s_nop 1
	v_add_f32_dpp v102, v103, v103 row_ror:8 row_mask:0xf bank_mask:0xf
	v_mov_b32_e32 v103, v102
	s_nop 1
	v_permlane16_swap_b32_e32 v102, v103
	v_add_f32_e32 v102, v102, v103
	v_mov_b32_e32 v103, v102
	s_nop 1
	v_permlane32_swap_b32_e32 v102, v103
	v_add_f32_e32 v102, v102, v103
	v_fmamk_f32 v104, v102, 0x3a800000, v110
	v_mul_f32_e32 v105, 0x4f800000, v104
	v_cmp_gt_f32_e32 vcc, s5, v104
	s_nop 1
	v_cndmask_b32_e32 v104, v104, v105, vcc
	v_sqrt_f32_e32 v105, v104
	s_nop 0
	v_add_u32_e32 v106, -1, v105
	v_add_u32_e32 v107, 1, v105
	v_fma_f32 v108, -v106, v105, v104
	v_fma_f32 v109, -v107, v105, v104
	v_cmp_ge_f32_e64 s[0:1], 0, v108
	s_nop 1
	v_cndmask_b32_e64 v105, v105, v106, s[0:1]
	v_cmp_lt_f32_e64 s[0:1], 0, v109
	s_nop 1
	v_cndmask_b32_e64 v105, v105, v107, s[0:1]
	v_mul_f32_e32 v106, 0x37800000, v105
	v_cndmask_b32_e32 v105, v105, v106, vcc
	v_cmp_class_f32_e32 vcc, v104, v111
	s_nop 1
	v_cndmask_b32_e32 v104, v105, v104, vcc
	v_div_scale_f32 v105, s[0:1], v104, v104, 1.0
	v_rcp_f32_e32 v107, v105
	v_div_scale_f32 v106, vcc, 1.0, v104, 1.0
	v_fma_f32 v108, -v105, v107, 1.0
	v_fmac_f32_e32 v107, v108, v107
	v_mul_f32_e32 v108, v106, v107
	v_fma_f32 v109, -v105, v108, v106
	v_fmac_f32_e32 v108, v109, v107
	v_fma_f32 v105, -v105, v108, v106
	v_div_fmas_f32 v105, v105, v107, v108
	v_div_fixup_f32 v104, v105, v104, 1.0
	v_pk_mul_f32 v[112:113], v[52:53], v[104:105] op_sel_hi:[1,0]
	v_pk_mul_f32 v[112:113], v[4:5], v[112:113]
	v_pk_fma_f32 v[112:113], v[20:21], v[112:113], v[36:37]
	v_pk_mul_f32 v[114:115], v[54:55], v[104:105] op_sel_hi:[1,0]
	v_pk_mul_f32 v[114:115], v[6:7], v[114:115]
	v_pk_fma_f32 v[114:115], v[22:23], v[114:115], v[38:39]
	v_cvt_pk_bf16_f32 v116, v112, v113
	v_cvt_pk_bf16_f32 v117, v114, v115
	global_store_dwordx2 v3, v[116:117], s[12:13]
	v_pk_mul_f32 v[112:113], v[56:57], v[104:105] op_sel_hi:[1,0]
	v_pk_mul_f32 v[112:113], v[8:9], v[112:113]
	v_pk_fma_f32 v[112:113], v[24:25], v[112:113], v[40:41]
	v_pk_mul_f32 v[114:115], v[58:59], v[104:105] op_sel_hi:[1,0]
	v_pk_mul_f32 v[114:115], v[10:11], v[114:115]
	v_pk_fma_f32 v[114:115], v[26:27], v[114:115], v[42:43]
	v_cvt_pk_bf16_f32 v118, v112, v113
	v_cvt_pk_bf16_f32 v119, v114, v115
	global_store_dwordx2 v3, v[118:119], s[12:13] offset:512
	v_pk_mul_f32 v[112:113], v[60:61], v[104:105] op_sel_hi:[1,0]
	v_pk_mul_f32 v[112:113], v[12:13], v[112:113]
	v_pk_fma_f32 v[112:113], v[28:29], v[112:113], v[44:45]
	v_pk_mul_f32 v[114:115], v[62:63], v[104:105] op_sel_hi:[1,0]
	v_pk_mul_f32 v[114:115], v[14:15], v[114:115]
	v_pk_fma_f32 v[114:115], v[30:31], v[114:115], v[46:47]
	v_cvt_pk_bf16_f32 v120, v112, v113
	v_cvt_pk_bf16_f32 v121, v114, v115
	global_store_dwordx2 v3, v[120:121], s[12:13] offset:1024
	v_pk_mul_f32 v[112:113], v[64:65], v[104:105] op_sel_hi:[1,0]
	v_pk_mul_f32 v[112:113], v[16:17], v[112:113]
	v_pk_fma_f32 v[112:113], v[32:33], v[112:113], v[48:49]
	v_pk_mul_f32 v[114:115], v[66:67], v[104:105] op_sel_hi:[1,0]
	v_pk_mul_f32 v[114:115], v[18:19], v[114:115]
	v_pk_fma_f32 v[114:115], v[34:35], v[114:115], v[50:51]
	v_cvt_pk_bf16_f32 v122, v112, v113
	v_cvt_pk_bf16_f32 v123, v114, v115
	global_store_dwordx2 v3, v[122:123], s[12:13] offset:1536
	s_add_u32 s12, s12, 0x800
	s_addc_u32 s13, s13, 0
	global_load_dwordx4 v[52:55], v2, s[8:9]
	global_load_dwordx4 v[56:59], v2, s[8:9] offset:1024
	global_load_dwordx4 v[60:63], v2, s[8:9] offset:2048
	global_load_dwordx4 v[64:67], v2, s[8:9] offset:3072
	s_cmp_lt_u32 s4, 27
	s_cselect_b32 s0, 0x1000, 0
	s_add_u32 s8, s8, s0
	s_addc_u32 s9, s9, 0
	s_waitcnt vmcnt(24)
	v_pk_mul_f32 v[100:101], v[68:69], v[68:69]
	v_pk_fma_f32 v[100:101], v[70:71], v[70:71], v[100:101]
	v_pk_fma_f32 v[100:101], v[72:73], v[72:73], v[100:101]
	v_pk_fma_f32 v[100:101], v[74:75], v[74:75], v[100:101]
	v_pk_fma_f32 v[100:101], v[76:77], v[76:77], v[100:101]
	v_pk_fma_f32 v[100:101], v[78:79], v[78:79], v[100:101]
	v_pk_fma_f32 v[100:101], v[80:81], v[80:81], v[100:101]
	v_pk_fma_f32 v[100:101], v[82:83], v[82:83], v[100:101]
	v_add_f32_e32 v102, v100, v101
	s_nop 1
	v_add_f32_dpp v103, v102, v102 quad_perm:[1,0,3,2] row_mask:0xf bank_mask:0xf
	s_nop 1
	v_add_f32_dpp v102, v103, v103 quad_perm:[2,3,0,1] row_mask:0xf bank_mask:0xf
	s_nop 1
	v_add_f32_dpp v103, v102, v102 row_ror:4 row_mask:0xf bank_mask:0xf
	s_nop 1
	v_add_f32_dpp v102, v103, v103 row_ror:8 row_mask:0xf bank_mask:0xf
	v_mov_b32_e32 v103, v102
	s_nop 1
	v_permlane16_swap_b32_e32 v102, v103
	v_add_f32_e32 v102, v102, v103
	v_mov_b32_e32 v103, v102
	s_nop 1
	v_permlane32_swap_b32_e32 v102, v103
	v_add_f32_e32 v102, v102, v103
	v_fmamk_f32 v104, v102, 0x3a800000, v110
	v_mul_f32_e32 v105, 0x4f800000, v104
	v_cmp_gt_f32_e32 vcc, s5, v104
	s_nop 1
	v_cndmask_b32_e32 v104, v104, v105, vcc
	v_sqrt_f32_e32 v105, v104
	s_nop 0
	v_add_u32_e32 v106, -1, v105
	v_add_u32_e32 v107, 1, v105
	v_fma_f32 v108, -v106, v105, v104
	v_fma_f32 v109, -v107, v105, v104
	v_cmp_ge_f32_e64 s[0:1], 0, v108
	s_nop 1
	v_cndmask_b32_e64 v105, v105, v106, s[0:1]
	v_cmp_lt_f32_e64 s[0:1], 0, v109
	s_nop 1
	v_cndmask_b32_e64 v105, v105, v107, s[0:1]
	v_mul_f32_e32 v106, 0x37800000, v105
	v_cndmask_b32_e32 v105, v105, v106, vcc
	v_cmp_class_f32_e32 vcc, v104, v111
	s_nop 1
	v_cndmask_b32_e32 v104, v105, v104, vcc
	v_div_scale_f32 v105, s[0:1], v104, v104, 1.0
	v_rcp_f32_e32 v107, v105
	v_div_scale_f32 v106, vcc, 1.0, v104, 1.0
	v_fma_f32 v108, -v105, v107, 1.0
	v_fmac_f32_e32 v107, v108, v107
	v_mul_f32_e32 v108, v106, v107
	v_fma_f32 v109, -v105, v108, v106
	v_fmac_f32_e32 v108, v109, v107
	v_fma_f32 v105, -v105, v108, v106
	v_div_fmas_f32 v105, v105, v107, v108
	v_div_fixup_f32 v104, v105, v104, 1.0
	v_pk_mul_f32 v[112:113], v[68:69], v[104:105] op_sel_hi:[1,0]
	v_pk_mul_f32 v[112:113], v[4:5], v[112:113]
	v_pk_fma_f32 v[112:113], v[20:21], v[112:113], v[36:37]
	v_pk_mul_f32 v[114:115], v[70:71], v[104:105] op_sel_hi:[1,0]
	v_pk_mul_f32 v[114:115], v[6:7], v[114:115]
	v_pk_fma_f32 v[114:115], v[22:23], v[114:115], v[38:39]
	v_cvt_pk_bf16_f32 v116, v112, v113
	v_cvt_pk_bf16_f32 v117, v114, v115
	global_store_dwordx2 v3, v[116:117], s[12:13]
	v_pk_mul_f32 v[112:113], v[72:73], v[104:105] op_sel_hi:[1,0]
	v_pk_mul_f32 v[112:113], v[8:9], v[112:113]
	v_pk_fma_f32 v[112:113], v[24:25], v[112:113], v[40:41]
	v_pk_mul_f32 v[114:115], v[74:75], v[104:105] op_sel_hi:[1,0]
	v_pk_mul_f32 v[114:115], v[10:11], v[114:115]
	v_pk_fma_f32 v[114:115], v[26:27], v[114:115], v[42:43]
	v_cvt_pk_bf16_f32 v118, v112, v113
	v_cvt_pk_bf16_f32 v119, v114, v115
	global_store_dwordx2 v3, v[118:119], s[12:13] offset:512
	v_pk_mul_f32 v[112:113], v[76:77], v[104:105] op_sel_hi:[1,0]
	v_pk_mul_f32 v[112:113], v[12:13], v[112:113]
	v_pk_fma_f32 v[112:113], v[28:29], v[112:113], v[44:45]
	v_pk_mul_f32 v[114:115], v[78:79], v[104:105] op_sel_hi:[1,0]
	v_pk_mul_f32 v[114:115], v[14:15], v[114:115]
	v_pk_fma_f32 v[114:115], v[30:31], v[114:115], v[46:47]
	v_cvt_pk_bf16_f32 v120, v112, v113
	v_cvt_pk_bf16_f32 v121, v114, v115
	global_store_dwordx2 v3, v[120:121], s[12:13] offset:1024
	v_pk_mul_f32 v[112:113], v[80:81], v[104:105] op_sel_hi:[1,0]
	v_pk_mul_f32 v[112:113], v[16:17], v[112:113]
	v_pk_fma_f32 v[112:113], v[32:33], v[112:113], v[48:49]
	v_pk_mul_f32 v[114:115], v[82:83], v[104:105] op_sel_hi:[1,0]
	v_pk_mul_f32 v[114:115], v[18:19], v[114:115]
	v_pk_fma_f32 v[114:115], v[34:35], v[114:115], v[50:51]
	v_cvt_pk_bf16_f32 v122, v112, v113
	v_cvt_pk_bf16_f32 v123, v114, v115
	global_store_dwordx2 v3, v[122:123], s[12:13] offset:1536
	s_add_u32 s12, s12, 0x800
	s_addc_u32 s13, s13, 0
	global_load_dwordx4 v[68:71], v2, s[8:9]
	global_load_dwordx4 v[72:75], v2, s[8:9] offset:1024
	global_load_dwordx4 v[76:79], v2, s[8:9] offset:2048
	global_load_dwordx4 v[80:83], v2, s[8:9] offset:3072
	s_cmp_lt_u32 s4, 26
	s_cselect_b32 s0, 0x1000, 0
	s_add_u32 s8, s8, s0
	s_addc_u32 s9, s9, 0
	s_waitcnt vmcnt(24)
	v_pk_mul_f32 v[100:101], v[84:85], v[84:85]
	v_pk_fma_f32 v[100:101], v[86:87], v[86:87], v[100:101]
	v_pk_fma_f32 v[100:101], v[88:89], v[88:89], v[100:101]
	v_pk_fma_f32 v[100:101], v[90:91], v[90:91], v[100:101]
	v_pk_fma_f32 v[100:101], v[92:93], v[92:93], v[100:101]
	v_pk_fma_f32 v[100:101], v[94:95], v[94:95], v[100:101]
	v_pk_fma_f32 v[100:101], v[96:97], v[96:97], v[100:101]
	v_pk_fma_f32 v[100:101], v[98:99], v[98:99], v[100:101]
	v_add_f32_e32 v102, v100, v101
	s_nop 1
	v_add_f32_dpp v103, v102, v102 quad_perm:[1,0,3,2] row_mask:0xf bank_mask:0xf
	s_nop 1
	v_add_f32_dpp v102, v103, v103 quad_perm:[2,3,0,1] row_mask:0xf bank_mask:0xf
	s_nop 1
	v_add_f32_dpp v103, v102, v102 row_ror:4 row_mask:0xf bank_mask:0xf
	s_nop 1
	v_add_f32_dpp v102, v103, v103 row_ror:8 row_mask:0xf bank_mask:0xf
	v_mov_b32_e32 v103, v102
	s_nop 1
	v_permlane16_swap_b32_e32 v102, v103
	v_add_f32_e32 v102, v102, v103
	v_mov_b32_e32 v103, v102
	s_nop 1
	v_permlane32_swap_b32_e32 v102, v103
	v_add_f32_e32 v102, v102, v103
	v_fmamk_f32 v104, v102, 0x3a800000, v110
	v_mul_f32_e32 v105, 0x4f800000, v104
	v_cmp_gt_f32_e32 vcc, s5, v104
	s_nop 1
	v_cndmask_b32_e32 v104, v104, v105, vcc
	v_sqrt_f32_e32 v105, v104
	s_nop 0
	v_add_u32_e32 v106, -1, v105
	v_add_u32_e32 v107, 1, v105
	v_fma_f32 v108, -v106, v105, v104
	v_fma_f32 v109, -v107, v105, v104
	v_cmp_ge_f32_e64 s[0:1], 0, v108
	s_nop 1
	v_cndmask_b32_e64 v105, v105, v106, s[0:1]
	v_cmp_lt_f32_e64 s[0:1], 0, v109
	s_nop 1
	v_cndmask_b32_e64 v105, v105, v107, s[0:1]
	v_mul_f32_e32 v106, 0x37800000, v105
	v_cndmask_b32_e32 v105, v105, v106, vcc
	v_cmp_class_f32_e32 vcc, v104, v111
	s_nop 1
	v_cndmask_b32_e32 v104, v105, v104, vcc
	v_div_scale_f32 v105, s[0:1], v104, v104, 1.0
	v_rcp_f32_e32 v107, v105
	v_div_scale_f32 v106, vcc, 1.0, v104, 1.0
	v_fma_f32 v108, -v105, v107, 1.0
	v_fmac_f32_e32 v107, v108, v107
	v_mul_f32_e32 v108, v106, v107
	v_fma_f32 v109, -v105, v108, v106
	v_fmac_f32_e32 v108, v109, v107
	v_fma_f32 v105, -v105, v108, v106
	v_div_fmas_f32 v105, v105, v107, v108
	v_div_fixup_f32 v104, v105, v104, 1.0
	v_pk_mul_f32 v[112:113], v[84:85], v[104:105] op_sel_hi:[1,0]
	v_pk_mul_f32 v[112:113], v[4:5], v[112:113]
	v_pk_fma_f32 v[112:113], v[20:21], v[112:113], v[36:37]
	v_pk_mul_f32 v[114:115], v[86:87], v[104:105] op_sel_hi:[1,0]
	v_pk_mul_f32 v[114:115], v[6:7], v[114:115]
	v_pk_fma_f32 v[114:115], v[22:23], v[114:115], v[38:39]
	v_cvt_pk_bf16_f32 v116, v112, v113
	v_cvt_pk_bf16_f32 v117, v114, v115
	global_store_dwordx2 v3, v[116:117], s[12:13]
	v_pk_mul_f32 v[112:113], v[88:89], v[104:105] op_sel_hi:[1,0]
	v_pk_mul_f32 v[112:113], v[8:9], v[112:113]
	v_pk_fma_f32 v[112:113], v[24:25], v[112:113], v[40:41]
	v_pk_mul_f32 v[114:115], v[90:91], v[104:105] op_sel_hi:[1,0]
	v_pk_mul_f32 v[114:115], v[10:11], v[114:115]
	v_pk_fma_f32 v[114:115], v[26:27], v[114:115], v[42:43]
	v_cvt_pk_bf16_f32 v118, v112, v113
	v_cvt_pk_bf16_f32 v119, v114, v115
	global_store_dwordx2 v3, v[118:119], s[12:13] offset:512
	v_pk_mul_f32 v[112:113], v[92:93], v[104:105] op_sel_hi:[1,0]
	v_pk_mul_f32 v[112:113], v[12:13], v[112:113]
	v_pk_fma_f32 v[112:113], v[28:29], v[112:113], v[44:45]
	v_pk_mul_f32 v[114:115], v[94:95], v[104:105] op_sel_hi:[1,0]
	v_pk_mul_f32 v[114:115], v[14:15], v[114:115]
	v_pk_fma_f32 v[114:115], v[30:31], v[114:115], v[46:47]
	v_cvt_pk_bf16_f32 v120, v112, v113
	v_cvt_pk_bf16_f32 v121, v114, v115
	global_store_dwordx2 v3, v[120:121], s[12:13] offset:1024
	v_pk_mul_f32 v[112:113], v[96:97], v[104:105] op_sel_hi:[1,0]
	v_pk_mul_f32 v[112:113], v[16:17], v[112:113]
	v_pk_fma_f32 v[112:113], v[32:33], v[112:113], v[48:49]
	v_pk_mul_f32 v[114:115], v[98:99], v[104:105] op_sel_hi:[1,0]
	v_pk_mul_f32 v[114:115], v[18:19], v[114:115]
	v_pk_fma_f32 v[114:115], v[34:35], v[114:115], v[50:51]
	v_cvt_pk_bf16_f32 v122, v112, v113
	v_cvt_pk_bf16_f32 v123, v114, v115
	global_store_dwordx2 v3, v[122:123], s[12:13] offset:1536
	s_add_u32 s12, s12, 0x800
	s_addc_u32 s13, s13, 0
	global_load_dwordx4 v[84:87], v2, s[8:9]
	global_load_dwordx4 v[88:91], v2, s[8:9] offset:1024
	global_load_dwordx4 v[92:95], v2, s[8:9] offset:2048
	global_load_dwordx4 v[96:99], v2, s[8:9] offset:3072
	s_cmp_lt_u32 s4, 25
	s_cselect_b32 s0, 0x1000, 0
	s_add_u32 s8, s8, s0
	s_addc_u32 s9, s9, 0
	s_waitcnt vmcnt(24)
	v_pk_mul_f32 v[100:101], v[124:125], v[124:125]
	v_pk_fma_f32 v[100:101], v[126:127], v[126:127], v[100:101]
	v_pk_fma_f32 v[100:101], v[128:129], v[128:129], v[100:101]
	v_pk_fma_f32 v[100:101], v[130:131], v[130:131], v[100:101]
	v_pk_fma_f32 v[100:101], v[132:133], v[132:133], v[100:101]
	v_pk_fma_f32 v[100:101], v[134:135], v[134:135], v[100:101]
	v_pk_fma_f32 v[100:101], v[136:137], v[136:137], v[100:101]
	v_pk_fma_f32 v[100:101], v[138:139], v[138:139], v[100:101]
	v_add_f32_e32 v102, v100, v101
	s_nop 1
	v_add_f32_dpp v103, v102, v102 quad_perm:[1,0,3,2] row_mask:0xf bank_mask:0xf
	s_nop 1
	v_add_f32_dpp v102, v103, v103 quad_perm:[2,3,0,1] row_mask:0xf bank_mask:0xf
	s_nop 1
	v_add_f32_dpp v103, v102, v102 row_ror:4 row_mask:0xf bank_mask:0xf
	s_nop 1
	v_add_f32_dpp v102, v103, v103 row_ror:8 row_mask:0xf bank_mask:0xf
	v_mov_b32_e32 v103, v102
	s_nop 1
	v_permlane16_swap_b32_e32 v102, v103
	v_add_f32_e32 v102, v102, v103
	v_mov_b32_e32 v103, v102
	s_nop 1
	v_permlane32_swap_b32_e32 v102, v103
	v_add_f32_e32 v102, v102, v103
	v_fmamk_f32 v104, v102, 0x3a800000, v110
	v_mul_f32_e32 v105, 0x4f800000, v104
	v_cmp_gt_f32_e32 vcc, s5, v104
	s_nop 1
	v_cndmask_b32_e32 v104, v104, v105, vcc
	v_sqrt_f32_e32 v105, v104
	s_nop 0
	v_add_u32_e32 v106, -1, v105
	v_add_u32_e32 v107, 1, v105
	v_fma_f32 v108, -v106, v105, v104
	v_fma_f32 v109, -v107, v105, v104
	v_cmp_ge_f32_e64 s[0:1], 0, v108
	s_nop 1
	v_cndmask_b32_e64 v105, v105, v106, s[0:1]
	v_cmp_lt_f32_e64 s[0:1], 0, v109
	s_nop 1
	v_cndmask_b32_e64 v105, v105, v107, s[0:1]
	v_mul_f32_e32 v106, 0x37800000, v105
	v_cndmask_b32_e32 v105, v105, v106, vcc
	v_cmp_class_f32_e32 vcc, v104, v111
	s_nop 1
	v_cndmask_b32_e32 v104, v105, v104, vcc
	v_div_scale_f32 v105, s[0:1], v104, v104, 1.0
	v_rcp_f32_e32 v107, v105
	v_div_scale_f32 v106, vcc, 1.0, v104, 1.0
	v_fma_f32 v108, -v105, v107, 1.0
	v_fmac_f32_e32 v107, v108, v107
	v_mul_f32_e32 v108, v106, v107
	v_fma_f32 v109, -v105, v108, v106
	v_fmac_f32_e32 v108, v109, v107
	v_fma_f32 v105, -v105, v108, v106
	v_div_fmas_f32 v105, v105, v107, v108
	v_div_fixup_f32 v104, v105, v104, 1.0
	v_pk_mul_f32 v[112:113], v[124:125], v[104:105] op_sel_hi:[1,0]
	v_pk_mul_f32 v[112:113], v[4:5], v[112:113]
	v_pk_fma_f32 v[112:113], v[20:21], v[112:113], v[36:37]
	v_pk_mul_f32 v[114:115], v[126:127], v[104:105] op_sel_hi:[1,0]
	v_pk_mul_f32 v[114:115], v[6:7], v[114:115]
	v_pk_fma_f32 v[114:115], v[22:23], v[114:115], v[38:39]
	v_cvt_pk_bf16_f32 v116, v112, v113
	v_cvt_pk_bf16_f32 v117, v114, v115
	global_store_dwordx2 v3, v[116:117], s[12:13]
	v_pk_mul_f32 v[112:113], v[128:129], v[104:105] op_sel_hi:[1,0]
	v_pk_mul_f32 v[112:113], v[8:9], v[112:113]
	v_pk_fma_f32 v[112:113], v[24:25], v[112:113], v[40:41]
	v_pk_mul_f32 v[114:115], v[130:131], v[104:105] op_sel_hi:[1,0]
	v_pk_mul_f32 v[114:115], v[10:11], v[114:115]
	v_pk_fma_f32 v[114:115], v[26:27], v[114:115], v[42:43]
	v_cvt_pk_bf16_f32 v118, v112, v113
	v_cvt_pk_bf16_f32 v119, v114, v115
	global_store_dwordx2 v3, v[118:119], s[12:13] offset:512
	v_pk_mul_f32 v[112:113], v[132:133], v[104:105] op_sel_hi:[1,0]
	v_pk_mul_f32 v[112:113], v[12:13], v[112:113]
	v_pk_fma_f32 v[112:113], v[28:29], v[112:113], v[44:45]
	v_pk_mul_f32 v[114:115], v[134:135], v[104:105] op_sel_hi:[1,0]
	v_pk_mul_f32 v[114:115], v[14:15], v[114:115]
	v_pk_fma_f32 v[114:115], v[30:31], v[114:115], v[46:47]
	v_cvt_pk_bf16_f32 v120, v112, v113
	v_cvt_pk_bf16_f32 v121, v114, v115
	global_store_dwordx2 v3, v[120:121], s[12:13] offset:1024
	v_pk_mul_f32 v[112:113], v[136:137], v[104:105] op_sel_hi:[1,0]
	v_pk_mul_f32 v[112:113], v[16:17], v[112:113]
	v_pk_fma_f32 v[112:113], v[32:33], v[112:113], v[48:49]
	v_pk_mul_f32 v[114:115], v[138:139], v[104:105] op_sel_hi:[1,0]
	v_pk_mul_f32 v[114:115], v[18:19], v[114:115]
	v_pk_fma_f32 v[114:115], v[34:35], v[114:115], v[50:51]
	v_cvt_pk_bf16_f32 v122, v112, v113
	v_cvt_pk_bf16_f32 v123, v114, v115
	global_store_dwordx2 v3, v[122:123], s[12:13] offset:1536
	s_add_u32 s12, s12, 0x800
	s_addc_u32 s13, s13, 0
	global_load_dwordx4 v[124:127], v2, s[8:9]
	global_load_dwordx4 v[128:131], v2, s[8:9] offset:1024
	global_load_dwordx4 v[132:135], v2, s[8:9] offset:2048
	global_load_dwordx4 v[136:139], v2, s[8:9] offset:3072
	s_cmp_lt_u32 s4, 24
	s_cselect_b32 s0, 0x1000, 0
	s_add_u32 s8, s8, s0
	s_addc_u32 s9, s9, 0
	s_add_i32 s4, s4, 4
	s_cmp_lt_u32 s4, 32
	s_cbranch_scc1 .Lnorm_fast_loop
